# non-temporal (nt) hint on the read-once f32 KV-cache loads of the sample attention units (keeps re-used bf16 K/V tiles in L2)
# speedup vs baseline: 1.0056x; 1.0056x over previous
.LBB0_785:
	s_or_b64 exec, exec, s[8:9]
	s_and_b32 s2, s5, 7
	s_ashr_i32 s17, s80, 3
	s_lshl_b32 s13, s2, 8
	s_add_i32 s2, s17, s25
	s_ashr_i32 s3, s2, 31
	s_lshl_b64 s[8:9], s[2:3], 20
	s_add_u32 s2, s88, s8
	s_addc_u32 s3, s89, s9
	s_lshl_b32 s12, s4, 6
	s_lshl_b32 s10, s4, 8
	s_add_u32 s14, s2, s10
	s_addc_u32 s15, s3, 0
	s_add_u32 s2, s90, s8
	s_addc_u32 s3, s91, s9
	s_add_u32 s10, s2, s10
	s_addc_u32 s11, s3, 0
	s_lshl_b32 s2, s17, 4
	s_ashr_i32 s3, s2, 31
	s_add_u32 s2, s2, 0x4000
	v_and_b32_e32 v19, 15, v18
	s_addc_u32 s3, s3, 0
	v_or_b32_e32 v2, s2, v19
	v_mov_b32_e32 v3, s3
	v_lshlrev_b64 v[2:3], 10, v[2:3]
	s_waitcnt vmcnt(0)
	v_ashrrev_i32_e32 v44, 2, v18
	v_lshl_add_u64 v[2:3], s[36:37], 0, v[2:3]
	s_lshl_b32 s18, s4, 7
	v_and_b32_e32 v4, -8, v44
	v_lshl_add_u64 v[2:3], v[2:3], 0, s[18:19]
	v_ashrrev_i32_e32 v5, 31, v4
	v_lshl_add_u64 v[2:3], v[4:5], 1, v[2:3]
	v_mov_b32_e32 v45, v0
	global_load_dwordx4 v[96:99], v[2:3], off
	global_load_dwordx4 v[10:13], v[2:3], off offset:32
	global_load_dwordx4 v[6:9], v[2:3], off offset:64
	s_nop 0
	global_load_dwordx4 v[2:5], v[2:3], off offset:96
	v_mul_f32_e32 v48, 0x3fb8aa3b, v1
	v_ashrrev_i32_e32 v36, 3, v45
	v_lshlrev_b32_e32 v14, 3, v45
	v_ashrrev_i32_e32 v37, 31, v36
	v_and_b32_e32 v38, 56, v14
	v_lshlrev_b64 v[16:17], 11, v[36:37]
	v_lshl_add_u64 v[20:21], s[14:15], 0, v[16:17]
	v_lshlrev_b32_e32 v14, 2, v38
	v_lshl_add_u64 v[24:25], v[20:21], 0, v[14:15]
	v_lshl_add_u64 v[28:29], s[10:11], 0, v[16:17]
	global_load_dwordx4 v[20:23], v[24:25], off nt
	s_nop 0
	global_load_dwordx4 v[24:27], v[24:25], off offset:16 nt
	v_lshl_add_u64 v[32:33], v[28:29], 0, v[14:15]
	global_load_dwordx4 v[28:31], v[32:33], off nt
	s_nop 0
	global_load_dwordx4 v[32:35], v[32:33], off offset:16 nt
	v_and_b32_e32 v37, 4, v45
	v_lshrrev_b32_e32 v39, 7, v45
	v_and_b32_e32 v1, 0x70, v45
	v_lshlrev_b32_e32 v40, 4, v45
	v_lshlrev_b32_e32 v41, 7, v36
	v_add_lshl_u32 v39, v37, v39, 10
	v_lshlrev_b32_e32 v36, 6, v36
	v_lshlrev_b32_e32 v37, 1, v38
	s_mov_b64 s[20:21], 0x20000
	v_and_b32_e32 v40, 48, v40
	v_and_b32_e32 v38, 0x3c0, v36
	v_bitop3_b32 v1, v37, v41, v1 bitop3:0xde
	v_lshl_add_u64 v[36:37], v[16:17], 0, s[20:21]
	s_mov_b64 s[20:21], 0x40000
	v_or3_b32 v42, v39, v38, v40
	v_lshl_add_u64 v[38:39], v[16:17], 0, s[20:21]
	v_lshl_add_u64 v[40:41], s[14:15], 0, v[36:37]
	v_lshl_add_u64 v[36:37], s[10:11], 0, v[36:37]
	v_add_u32_e32 v151, 0, v42
	v_lshl_add_u64 v[42:43], s[14:15], 0, v[38:39]
	v_lshl_add_u64 v[40:41], v[40:41], 0, v[14:15]
	v_add_u32_e32 v150, 0, v1
	v_lshl_add_u64 v[38:39], s[10:11], 0, v[38:39]
	v_lshl_add_u64 v[36:37], v[36:37], 0, v[14:15]
	v_lshl_add_u64 v[42:43], v[42:43], 0, v[14:15]
	global_load_dwordx4 v[104:107], v[40:41], off offset:16 nt
	global_load_dwordx4 v[100:103], v[40:41], off nt
	global_load_dwordx4 v[120:123], v[36:37], off offset:16 nt
	global_load_dwordx4 v[116:119], v[36:37], off nt
	v_lshl_add_u64 v[38:39], v[38:39], 0, v[14:15]
	v_ashrrev_i32_e32 v1, 5, v18
	v_lshrrev_b32_e32 v14, 1, v18
	v_lshlrev_b32_e32 v152, 2, v19
	v_lshlrev_b32_e32 v19, 3, v18
	v_bitop3_b32 v14, v14, v1, 7 bitop3:0x6c
	v_and_b32_e32 v145, 31, v18
	v_readlane_b32 s17, v250, 35
	v_lshlrev_b32_e32 v149, 4, v1
	v_ashrrev_i32_e32 v144, 3, v18
	v_cmp_gt_u32_e64 s[38:39], 32, v18
	s_add_u32 s10, s81, s18
	s_addc_u32 s11, s82, 0
	s_add_u32 s14, s30, s18
	s_addc_u32 s15, s83, 0
	v_lshl_add_u64 v[16:17], s[8:9], 0, v[16:17]
	s_mov_b32 s4, 1
	v_mov_b32_e32 v49, v48
	v_mov_b32_e32 v50, v48
	v_mov_b32_e32 v51, v48
	v_mov_b32_e32 v52, v48
	v_mov_b32_e32 v53, v48
	v_mov_b32_e32 v54, v48
	v_mov_b32_e32 v55, v48
	v_mov_b32_e32 v56, v48
	v_mov_b32_e32 v57, v48
	v_mov_b32_e32 v58, v48
	v_mov_b32_e32 v59, v48
	v_mov_b32_e32 v60, v48
	v_mov_b32_e32 v61, v48
	v_mov_b32_e32 v62, v48
	s_waitcnt vmcnt(7)
	v_cvt_pk_bf16_f32 v20, v20, v21
	v_cvt_pk_bf16_f32 v21, v22, v23
	s_waitcnt vmcnt(6)
	v_cvt_pk_bf16_f32 v22, v24, v25
	v_cvt_pk_bf16_f32 v23, v26, v27
	ds_write_b128 v150, v[20:23]
	s_waitcnt vmcnt(5)
	v_cvt_pk_bf16_f32 v20, v28, v29
	v_cvt_pk_bf16_f32 v21, v30, v31
	s_waitcnt vmcnt(4)
	v_cvt_pk_bf16_f32 v22, v32, v33
	v_cvt_pk_bf16_f32 v23, v34, v35
	global_load_dwordx4 v[108:111], v[42:43], off offset:16 nt
	global_load_dwordx4 v[112:115], v[42:43], off nt
	ds_write_b128 v151, v[20:23] offset:32768
	global_load_dwordx4 v[124:127], v[38:39], off offset:16 nt
	global_load_dwordx4 v[128:131], v[38:39], off nt
	v_and_b32_e32 v25, 24, v19
	v_lshlrev_b32_e32 v19, 4, v18
	v_lshlrev_b32_e32 v21, 4, v14
	v_lshlrev_b32_e32 v14, 1, v18
	v_and_b32_e32 v19, 0xc0, v19
	v_lshlrev_b32_e32 v20, 7, v145
	v_and_b32_e32 v14, 32, v14
	v_lshl_or_b32 v19, v1, 8, v19
	v_xor_b32_e32 v22, 32, v21
	v_xor_b32_e32 v23, 64, v21
	v_xor_b32_e32 v24, 0x60, v21
	v_or3_b32 v26, v19, v14, v25
	v_add_u32_e32 v14, 0, v20
	v_add_u32_e32 v156, v21, v14
	v_add_u32_e32 v155, v22, v14
	v_add_u32_e32 v154, v23, v14
	v_add_u32_e32 v153, v24, v14
	v_add_u32_e32 v14, s17, v152
	v_sub_u32_e32 v157, v14, v149
	v_add_u32_e32 v14, s93, v144
	v_lshrrev_b32_e32 v19, 1, v14
	v_xor_b32_e32 v27, v19, v18
	v_min_i32_e32 v18, 15, v14
	v_ashrrev_i32_e32 v19, 31, v18
	v_lshl_add_u64 v[18:19], s[2:3], 0, v[18:19]
	v_lshlrev_b64 v[18:19], 10, v[18:19]
	v_lshlrev_b32_e32 v14, 4, v27
	v_lshl_add_u64 v[18:19], s[10:11], 0, v[18:19]
	v_and_b32_e32 v14, 0x70, v14
	v_readlane_b32 s10, v250, 31
	v_lshl_add_u64 v[132:133], v[18:19], 0, v[14:15]
	s_add_i32 s17, 0, 0x10400
	v_add_u32_e32 v14, s10, v44
	v_min_i32_e32 v18, 15, v14
	v_ashrrev_i32_e32 v19, 31, v18
	v_lshl_add_u64 v[18:19], s[2:3], 0, v[18:19]
	v_lshlrev_b64 v[18:19], 10, v[18:19]
	v_readlane_b32 s10, v250, 33
	v_lshl_add_u64 v[18:19], s[14:15], 0, v[18:19]
	s_lshl_b32 s18, s10, 1
	v_lshl_add_u64 v[18:19], v[18:19], 0, s[18:19]
	v_lshlrev_b32_e32 v14, 1, v25
	s_add_i32 s10, 0, 0x2000
	v_lshl_add_u64 v[134:135], v[18:19], 0, v[14:15]
	v_add_u32_e32 v14, s10, v20
	v_readlane_b32 s10, v250, 37
	v_add_u32_e32 v158, v21, v14
	v_add_u32_e32 v159, v22, v14
	v_add_u32_e32 v160, v23, v14
	v_add_u32_e32 v161, v24, v14
	v_add_u32_e32 v14, s10, v152
	v_sub_u32_e32 v162, v14, v149
	v_and_b32_e32 v14, 7, v45
	v_lshlrev_b32_e32 v14, 5, v14
	v_lshl_add_u32 v146, v145, 2, s17
	s_add_i32 s17, 0, 0x8000
	s_add_i32 s10, 0, 0xa000
	v_or3_b32 v16, v16, s13, v14
	v_mov_b32_e32 v28, v15
	v_mov_b32_e32 v29, v15
	s_waitcnt lgkmcnt(0)
	v_add_u32_e32 v147, s17, v26
	v_add_u32_e32 v163, s10, v26
	v_lshl_add_u64 v[136:137], s[88:89], 0, v[16:17]
	v_lshl_add_u64 v[138:139], s[90:91], 0, v[16:17]
	v_mov_b32_e32 v14, v15
	v_mov_b32_e32 v16, v15
	v_mov_b32_e32 v17, v15
	v_mov_b32_e32 v18, v15
	v_mov_b32_e32 v19, v15
	v_mov_b32_e32 v20, v15
	v_mov_b32_e32 v21, v15
	v_mov_b32_e32 v22, v15
	v_mov_b32_e32 v23, v15
	v_mov_b32_e32 v24, v15
	v_mov_b32_e32 v25, v15
	v_mov_b32_e32 v26, v15
	v_mov_b32_e32 v27, v15
	v_mov_b64_e32 v[46:47], v[28:29]
	v_mov_b64_e32 v[44:45], v[26:27]
	v_mov_b64_e32 v[42:43], v[24:25]
	v_mov_b64_e32 v[40:41], v[22:23]
	v_mov_b64_e32 v[38:39], v[20:21]
	v_mov_b64_e32 v[36:37], v[18:19]
	v_mov_b64_e32 v[34:35], v[16:17]
	v_mov_b64_e32 v[32:33], v[14:15]
	v_mov_b64_e32 v[30:31], v[28:29]
	v_mov_b32_e32 v63, v48
	s_mov_b32 s13, 0
	v_mov_b32_e32 v148, 0
	s_mov_b64 s[8:9], 0
	v_mov_b64_e32 v[28:29], v[26:27]
	v_mov_b64_e32 v[26:27], v[24:25]
	v_mov_b64_e32 v[24:25], v[22:23]
	v_mov_b64_e32 v[22:23], v[20:21]
	v_mov_b64_e32 v[20:21], v[18:19]
	v_mov_b64_e32 v[18:19], v[16:17]
	v_mov_b64_e32 v[16:17], v[14:15]
	s_waitcnt lgkmcnt(0)
	s_barrier
	s_branch .LBB0_787

.LBB0_787:
	s_cmp_eq_u32 s8, 0xc0000
	s_cselect_b64 s[10:11], -1, 0
	s_cmp_lg_u32 s8, 0xc0000
	s_waitcnt vmcnt(6)
	v_cvt_pk_bf16_f32 v64, v100, v101
	v_cvt_pk_bf16_f32 v65, v102, v103
	v_cvt_pk_bf16_f32 v66, v104, v105
	v_cvt_pk_bf16_f32 v67, v106, v107
	s_cselect_b64 s[20:21], -1, 0
	s_and_b64 vcc, exec, s[10:11]
	v_lshl_add_u64 v[142:143], v[136:137], 0, s[8:9]
	v_lshl_add_u64 v[140:141], v[138:139], 0, s[8:9]
	ds_write_b128 v150, v[64:67] offset:8192
	s_waitcnt vmcnt(4)
	v_cvt_pk_bf16_f32 v64, v116, v117
	v_cvt_pk_bf16_f32 v65, v118, v119
	v_cvt_pk_bf16_f32 v66, v120, v121
	v_cvt_pk_bf16_f32 v67, v122, v123
	ds_write_b128 v151, v[64:67] offset:40960
	s_cbranch_vccnz .LBB0_789
	v_add_co_u32_e32 v68, vcc, 0x60000, v142
	v_lshl_add_u64 v[64:65], v[142:143], 0, s[94:95]
	s_nop 0
	v_addc_co_u32_e32 v69, vcc, 0, v143, vcc
	global_load_dwordx4 v[100:103], v[68:69], off nt
	global_load_dwordx4 v[104:107], v[64:65], off offset:16 nt
	v_add_co_u32_e32 v64, vcc, 0x60000, v140
	v_lshl_add_u64 v[66:67], v[140:141], 0, s[94:95]
	s_nop 0
	v_addc_co_u32_e32 v65, vcc, 0, v141, vcc
	global_load_dwordx4 v[116:119], v[64:65], off nt
	global_load_dwordx4 v[120:123], v[66:67], off offset:16 nt

.LBB0_807:
	v_add_co_u32_e32 v68, vcc, 0x80000, v142
	v_lshl_add_u64 v[64:65], v[142:143], 0, s[96:97]
	s_nop 0
	v_addc_co_u32_e32 v69, vcc, 0, v143, vcc
	global_load_dwordx4 v[112:115], v[68:69], off nt
	global_load_dwordx4 v[108:111], v[64:65], off offset:16 nt
	v_add_co_u32_e32 v64, vcc, 0x80000, v140
	v_lshl_add_u64 v[66:67], v[140:141], 0, s[96:97]
	s_nop 0
	v_addc_co_u32_e32 v65, vcc, 0, v141, vcc
	global_load_dwordx4 v[128:131], v[64:65], off nt
	global_load_dwordx4 v[124:127], v[66:67], off offset:16 nt
	s_and_b64 vcc, exec, s[42:43]
	s_cbranch_vccnz .LBB0_804

.LBB0_942:
	s_or_b64 exec, exec, s[2:3]
	s_and_b32 s0, s5, 7
	s_ashr_i32 s2, s52, 3
	s_lshl_b32 s13, s0, 8
	s_add_i32 s0, s2, s25
	s_ashr_i32 s1, s0, 31
	s_lshl_b64 s[8:9], s[0:1], 20
	s_add_u32 s0, s88, s8
	s_addc_u32 s1, s89, s9
	s_lshl_b32 s12, s4, 6
	s_lshl_b32 s3, s4, 8
	s_add_u32 s10, s0, s3
	s_addc_u32 s11, s1, 0
	s_add_u32 s0, s90, s8
	s_addc_u32 s1, s91, s9
	s_add_u32 s0, s0, s3
	s_addc_u32 s1, s1, 0
	s_lshl_b32 s2, s2, 4
	s_ashr_i32 s3, s2, 31
	s_add_u32 s2, s2, 0x4000
	v_and_b32_e32 v19, 15, v18
	s_addc_u32 s3, s3, 0
	v_or_b32_e32 v2, s2, v19
	v_mov_b32_e32 v3, s3
	v_lshlrev_b64 v[2:3], 10, v[2:3]
	s_waitcnt vmcnt(0)
	v_ashrrev_i32_e32 v44, 2, v18
	v_lshl_add_u64 v[2:3], s[36:37], 0, v[2:3]
	s_lshl_b32 s18, s4, 7
	v_and_b32_e32 v4, -8, v44
	v_lshl_add_u64 v[2:3], v[2:3], 0, s[18:19]
	v_ashrrev_i32_e32 v5, 31, v4
	v_lshl_add_u64 v[2:3], v[4:5], 1, v[2:3]
	v_mov_b32_e32 v45, v0
	global_load_dwordx4 v[96:99], v[2:3], off
	global_load_dwordx4 v[10:13], v[2:3], off offset:32
	global_load_dwordx4 v[6:9], v[2:3], off offset:64
	s_nop 0
	global_load_dwordx4 v[2:5], v[2:3], off offset:96
	s_waitcnt vmcnt(4)
	v_mul_f32_e32 v48, 0x3fb8aa3b, v1
	v_ashrrev_i32_e32 v36, 3, v45
	v_lshlrev_b32_e32 v14, 3, v45
	v_ashrrev_i32_e32 v37, 31, v36
	v_and_b32_e32 v38, 56, v14
	v_lshlrev_b64 v[16:17], 11, v[36:37]
	v_lshl_add_u64 v[20:21], s[10:11], 0, v[16:17]
	v_lshlrev_b32_e32 v14, 2, v38
	v_lshl_add_u64 v[24:25], v[20:21], 0, v[14:15]
	v_lshl_add_u64 v[28:29], s[0:1], 0, v[16:17]
	global_load_dwordx4 v[20:23], v[24:25], off nt
	s_nop 0
	global_load_dwordx4 v[24:27], v[24:25], off offset:16 nt
	v_lshl_add_u64 v[32:33], v[28:29], 0, v[14:15]
	global_load_dwordx4 v[28:31], v[32:33], off nt
	s_nop 0
	global_load_dwordx4 v[32:35], v[32:33], off offset:16 nt
	v_and_b32_e32 v37, 4, v45
	v_lshrrev_b32_e32 v39, 7, v45
	v_and_b32_e32 v1, 0x70, v45
	v_lshlrev_b32_e32 v40, 4, v45
	v_lshlrev_b32_e32 v41, 7, v36
	v_add_lshl_u32 v39, v37, v39, 10
	v_lshlrev_b32_e32 v36, 6, v36
	v_lshlrev_b32_e32 v37, 1, v38
	s_mov_b64 s[20:21], 0x20000
	v_and_b32_e32 v40, 48, v40
	v_and_b32_e32 v38, 0x3c0, v36
	v_bitop3_b32 v1, v37, v41, v1 bitop3:0xde
	v_lshl_add_u64 v[36:37], v[16:17], 0, s[20:21]
	s_mov_b64 s[20:21], 0x40000
	v_or3_b32 v42, v39, v38, v40
	v_lshl_add_u64 v[38:39], v[16:17], 0, s[20:21]
	v_lshl_add_u64 v[40:41], s[10:11], 0, v[36:37]
	v_lshl_add_u64 v[36:37], s[0:1], 0, v[36:37]
	v_add_u32_e32 v151, 0, v42
	v_lshl_add_u64 v[42:43], s[10:11], 0, v[38:39]
	v_lshl_add_u64 v[40:41], v[40:41], 0, v[14:15]
	v_add_u32_e32 v150, 0, v1
	v_lshl_add_u64 v[38:39], s[0:1], 0, v[38:39]
	v_lshl_add_u64 v[36:37], v[36:37], 0, v[14:15]
	v_lshl_add_u64 v[42:43], v[42:43], 0, v[14:15]
	global_load_dwordx4 v[104:107], v[40:41], off offset:16 nt
	global_load_dwordx4 v[100:103], v[40:41], off nt
	global_load_dwordx4 v[120:123], v[36:37], off offset:16 nt
	global_load_dwordx4 v[116:119], v[36:37], off nt
	v_lshl_add_u64 v[38:39], v[38:39], 0, v[14:15]
	v_ashrrev_i32_e32 v1, 5, v18
	v_lshrrev_b32_e32 v14, 1, v18
	v_lshlrev_b32_e32 v152, 2, v19
	v_lshlrev_b32_e32 v19, 3, v18
	v_bitop3_b32 v14, v14, v1, 7 bitop3:0x6c
	v_and_b32_e32 v145, 31, v18
	v_readlane_b32 s17, v250, 35
	v_lshlrev_b32_e32 v149, 4, v1
	v_ashrrev_i32_e32 v144, 3, v18
	v_cmp_gt_u32_e64 s[0:1], 32, v18
	s_add_u32 s10, s81, s18
	s_addc_u32 s11, s82, 0
	s_add_u32 s20, s30, s18
	s_addc_u32 s21, s83, 0
	v_lshl_add_u64 v[16:17], s[8:9], 0, v[16:17]
	s_mov_b32 s4, 1
	v_mov_b32_e32 v49, v48
	v_mov_b32_e32 v50, v48
	v_mov_b32_e32 v51, v48
	v_mov_b32_e32 v52, v48
	v_mov_b32_e32 v53, v48
	v_mov_b32_e32 v54, v48
	v_mov_b32_e32 v55, v48
	v_mov_b32_e32 v56, v48
	v_mov_b32_e32 v57, v48
	v_mov_b32_e32 v58, v48
	v_mov_b32_e32 v59, v48
	v_mov_b32_e32 v60, v48
	v_mov_b32_e32 v61, v48
	v_mov_b32_e32 v62, v48
	s_waitcnt vmcnt(7)
	v_cvt_pk_bf16_f32 v20, v20, v21
	v_cvt_pk_bf16_f32 v21, v22, v23
	s_waitcnt vmcnt(6)
	v_cvt_pk_bf16_f32 v22, v24, v25
	v_cvt_pk_bf16_f32 v23, v26, v27
	ds_write_b128 v150, v[20:23]
	s_waitcnt vmcnt(5)
	v_cvt_pk_bf16_f32 v20, v28, v29
	v_cvt_pk_bf16_f32 v21, v30, v31
	s_waitcnt vmcnt(4)
	v_cvt_pk_bf16_f32 v22, v32, v33
	v_cvt_pk_bf16_f32 v23, v34, v35
	global_load_dwordx4 v[108:111], v[42:43], off offset:16 nt
	global_load_dwordx4 v[112:115], v[42:43], off nt
	ds_write_b128 v151, v[20:23] offset:32768
	global_load_dwordx4 v[124:127], v[38:39], off offset:16 nt
	global_load_dwordx4 v[128:131], v[38:39], off nt
	v_and_b32_e32 v25, 24, v19
	v_lshlrev_b32_e32 v19, 4, v18
	v_lshlrev_b32_e32 v21, 4, v14
	v_lshlrev_b32_e32 v14, 1, v18
	v_and_b32_e32 v19, 0xc0, v19
	v_lshlrev_b32_e32 v20, 7, v145
	v_and_b32_e32 v14, 32, v14
	v_lshl_or_b32 v19, v1, 8, v19
	v_xor_b32_e32 v22, 32, v21
	v_xor_b32_e32 v23, 64, v21
	v_xor_b32_e32 v24, 0x60, v21
	v_or3_b32 v26, v19, v14, v25
	v_add_u32_e32 v14, 0, v20
	v_add_u32_e32 v156, v21, v14
	v_add_u32_e32 v155, v22, v14
	v_add_u32_e32 v154, v23, v14
	v_add_u32_e32 v153, v24, v14
	v_add_u32_e32 v14, s17, v152
	v_sub_u32_e32 v157, v14, v149
	v_add_u32_e32 v14, s93, v144
	v_lshrrev_b32_e32 v19, 1, v14
	v_xor_b32_e32 v27, v19, v18
	v_min_i32_e32 v18, 15, v14
	v_ashrrev_i32_e32 v19, 31, v18
	v_lshl_add_u64 v[18:19], s[2:3], 0, v[18:19]
	v_lshlrev_b64 v[18:19], 10, v[18:19]
	v_lshlrev_b32_e32 v14, 4, v27
	v_lshl_add_u64 v[18:19], s[10:11], 0, v[18:19]
	v_and_b32_e32 v14, 0x70, v14
	v_readlane_b32 s10, v250, 31
	v_lshl_add_u64 v[132:133], v[18:19], 0, v[14:15]
	s_add_i32 s17, 0, 0x10400
	v_add_u32_e32 v14, s10, v44
	v_min_i32_e32 v18, 15, v14
	v_ashrrev_i32_e32 v19, 31, v18
	v_lshl_add_u64 v[18:19], s[2:3], 0, v[18:19]
	v_lshlrev_b64 v[18:19], 10, v[18:19]
	v_readlane_b32 s10, v250, 33
	v_lshl_add_u64 v[18:19], s[20:21], 0, v[18:19]
	s_lshl_b32 s18, s10, 1
	v_lshl_add_u64 v[18:19], v[18:19], 0, s[18:19]
	v_lshlrev_b32_e32 v14, 1, v25
	s_add_i32 s10, 0, 0x2000
	v_lshl_add_u64 v[134:135], v[18:19], 0, v[14:15]
	v_add_u32_e32 v14, s10, v20
	v_readlane_b32 s10, v250, 37
	v_add_u32_e32 v158, v21, v14
	v_add_u32_e32 v159, v22, v14
	v_add_u32_e32 v160, v23, v14
	v_add_u32_e32 v161, v24, v14
	v_add_u32_e32 v14, s10, v152
	v_sub_u32_e32 v162, v14, v149
	v_and_b32_e32 v14, 7, v45
	v_lshlrev_b32_e32 v14, 5, v14
	v_lshl_add_u32 v146, v145, 2, s17
	s_add_i32 s17, 0, 0x8000
	s_add_i32 s10, 0, 0xa000
	v_or3_b32 v16, v16, s13, v14
	v_mov_b32_e32 v28, v15
	v_mov_b32_e32 v29, v15
	s_waitcnt lgkmcnt(0)
	v_add_u32_e32 v147, s17, v26
	v_add_u32_e32 v163, s10, v26
	v_lshl_add_u64 v[136:137], s[88:89], 0, v[16:17]
	v_lshl_add_u64 v[138:139], s[90:91], 0, v[16:17]
	v_mov_b32_e32 v14, v15
	v_mov_b32_e32 v16, v15
	v_mov_b32_e32 v17, v15
	v_mov_b32_e32 v18, v15
	v_mov_b32_e32 v19, v15
	v_mov_b32_e32 v20, v15
	v_mov_b32_e32 v21, v15
	v_mov_b32_e32 v22, v15
	v_mov_b32_e32 v23, v15
	v_mov_b32_e32 v24, v15
	v_mov_b32_e32 v25, v15
	v_mov_b32_e32 v26, v15
	v_mov_b32_e32 v27, v15
	v_mov_b64_e32 v[46:47], v[28:29]
	v_mov_b64_e32 v[44:45], v[26:27]
	v_mov_b64_e32 v[42:43], v[24:25]
	v_mov_b64_e32 v[40:41], v[22:23]
	v_mov_b64_e32 v[38:39], v[20:21]
	v_mov_b64_e32 v[36:37], v[18:19]
	v_mov_b64_e32 v[34:35], v[16:17]
	v_mov_b64_e32 v[32:33], v[14:15]
	v_mov_b64_e32 v[30:31], v[28:29]
	v_mov_b32_e32 v63, v48
	s_mov_b32 s13, 0
	v_mov_b32_e32 v148, 0
	s_mov_b64 s[8:9], 0
	v_mov_b64_e32 v[28:29], v[26:27]
	v_mov_b64_e32 v[26:27], v[24:25]
	v_mov_b64_e32 v[24:25], v[22:23]
	v_mov_b64_e32 v[22:23], v[20:21]
	v_mov_b64_e32 v[20:21], v[18:19]
	v_mov_b64_e32 v[18:19], v[16:17]
	v_mov_b64_e32 v[16:17], v[14:15]
	s_waitcnt lgkmcnt(0)
	s_barrier
	s_branch .LBB0_944

.LBB0_964:
	v_add_co_u32_e32 v68, vcc, 0x80000, v142
	v_lshl_add_u64 v[64:65], v[142:143], 0, s[96:97]
	s_nop 0
	v_addc_co_u32_e32 v69, vcc, 0, v143, vcc
	global_load_dwordx4 v[112:115], v[68:69], off nt
	global_load_dwordx4 v[108:111], v[64:65], off offset:16 nt
	v_add_co_u32_e32 v64, vcc, 0x80000, v140
	v_lshl_add_u64 v[66:67], v[140:141], 0, s[96:97]
	s_nop 0
	v_addc_co_u32_e32 v65, vcc, 0, v141, vcc
	global_load_dwordx4 v[128:131], v[64:65], off nt
	global_load_dwordx4 v[124:127], v[66:67], off offset:16 nt
	s_and_b64 vcc, exec, s[40:41]
	s_cbranch_vccnz .LBB0_961

.LBB0_1108:
	s_or_b64 exec, exec, s[2:3]
	s_and_b32 s0, s5, 7
	s_ashr_i32 s2, s52, 3
	s_lshl_b32 s13, s0, 8
	s_add_i32 s0, s2, s25
	s_ashr_i32 s1, s0, 31
	s_lshl_b64 s[8:9], s[0:1], 20
	s_add_u32 s0, s88, s8
	s_addc_u32 s1, s89, s9
	s_lshl_b32 s12, s4, 6
	s_lshl_b32 s3, s4, 8
	s_add_u32 s10, s0, s3
	s_addc_u32 s11, s1, 0
	s_add_u32 s0, s90, s8
	s_addc_u32 s1, s91, s9
	s_add_u32 s0, s0, s3
	s_addc_u32 s1, s1, 0
	s_lshl_b32 s2, s2, 4
	s_ashr_i32 s3, s2, 31
	s_add_u32 s2, s2, 0x4000
	v_and_b32_e32 v19, 15, v18
	s_addc_u32 s3, s3, 0
	v_or_b32_e32 v2, s2, v19
	v_mov_b32_e32 v3, s3
	v_lshlrev_b64 v[2:3], 10, v[2:3]
	s_waitcnt vmcnt(0)
	v_ashrrev_i32_e32 v44, 2, v18
	v_lshl_add_u64 v[2:3], s[36:37], 0, v[2:3]
	s_lshl_b32 s18, s4, 7
	v_and_b32_e32 v4, -8, v44
	v_lshl_add_u64 v[2:3], v[2:3], 0, s[18:19]
	v_ashrrev_i32_e32 v5, 31, v4
	v_lshl_add_u64 v[2:3], v[4:5], 1, v[2:3]
	v_mov_b32_e32 v45, v0
	global_load_dwordx4 v[96:99], v[2:3], off
	global_load_dwordx4 v[10:13], v[2:3], off offset:32
	global_load_dwordx4 v[6:9], v[2:3], off offset:64
	s_nop 0
	global_load_dwordx4 v[2:5], v[2:3], off offset:96
	v_mul_f32_e32 v48, 0x3fb8aa3b, v1
	v_ashrrev_i32_e32 v36, 3, v45
	v_lshlrev_b32_e32 v14, 3, v45
	v_ashrrev_i32_e32 v37, 31, v36
	v_and_b32_e32 v38, 56, v14
	v_lshlrev_b64 v[16:17], 11, v[36:37]
	v_lshl_add_u64 v[20:21], s[10:11], 0, v[16:17]
	v_lshlrev_b32_e32 v14, 2, v38
	v_lshl_add_u64 v[24:25], v[20:21], 0, v[14:15]
	v_lshl_add_u64 v[28:29], s[0:1], 0, v[16:17]
	global_load_dwordx4 v[20:23], v[24:25], off nt
	s_nop 0
	global_load_dwordx4 v[24:27], v[24:25], off offset:16 nt
	v_lshl_add_u64 v[32:33], v[28:29], 0, v[14:15]
	global_load_dwordx4 v[28:31], v[32:33], off nt
	s_nop 0
	global_load_dwordx4 v[32:35], v[32:33], off offset:16 nt
	v_and_b32_e32 v37, 4, v45
	v_lshrrev_b32_e32 v39, 7, v45
	v_and_b32_e32 v1, 0x70, v45
	v_lshlrev_b32_e32 v40, 4, v45
	v_lshlrev_b32_e32 v41, 7, v36
	v_add_lshl_u32 v39, v37, v39, 10
	v_lshlrev_b32_e32 v36, 6, v36
	v_lshlrev_b32_e32 v37, 1, v38
	s_mov_b64 s[20:21], 0x20000
	v_and_b32_e32 v40, 48, v40
	v_and_b32_e32 v38, 0x3c0, v36
	v_bitop3_b32 v1, v37, v41, v1 bitop3:0xde
	v_lshl_add_u64 v[36:37], v[16:17], 0, s[20:21]
	s_mov_b64 s[20:21], 0x40000
	v_or3_b32 v42, v39, v38, v40
	v_lshl_add_u64 v[38:39], v[16:17], 0, s[20:21]
	v_lshl_add_u64 v[40:41], s[10:11], 0, v[36:37]
	v_lshl_add_u64 v[36:37], s[0:1], 0, v[36:37]
	v_add_u32_e32 v151, 0, v42
	v_lshl_add_u64 v[42:43], s[10:11], 0, v[38:39]
	v_lshl_add_u64 v[40:41], v[40:41], 0, v[14:15]
	v_add_u32_e32 v150, 0, v1
	v_lshl_add_u64 v[38:39], s[0:1], 0, v[38:39]
	v_lshl_add_u64 v[36:37], v[36:37], 0, v[14:15]
	v_lshl_add_u64 v[42:43], v[42:43], 0, v[14:15]
	global_load_dwordx4 v[104:107], v[40:41], off offset:16 nt
	global_load_dwordx4 v[100:103], v[40:41], off nt
	global_load_dwordx4 v[120:123], v[36:37], off offset:16 nt
	global_load_dwordx4 v[116:119], v[36:37], off nt
	v_lshl_add_u64 v[38:39], v[38:39], 0, v[14:15]
	v_ashrrev_i32_e32 v1, 5, v18
	v_lshrrev_b32_e32 v14, 1, v18
	v_lshlrev_b32_e32 v152, 2, v19
	v_lshlrev_b32_e32 v19, 3, v18
	v_bitop3_b32 v14, v14, v1, 7 bitop3:0x6c
	v_and_b32_e32 v145, 31, v18
	v_readlane_b32 s17, v250, 35
	v_lshlrev_b32_e32 v149, 4, v1
	v_ashrrev_i32_e32 v144, 3, v18
	v_cmp_gt_u32_e64 s[0:1], 32, v18
	s_add_u32 s10, s81, s18
	s_addc_u32 s11, s82, 0
	s_add_u32 s20, s30, s18
	s_addc_u32 s21, s83, 0
	v_lshl_add_u64 v[16:17], s[8:9], 0, v[16:17]
	s_mov_b32 s4, 1
	v_mov_b32_e32 v49, v48
	v_mov_b32_e32 v50, v48
	v_mov_b32_e32 v51, v48
	v_mov_b32_e32 v52, v48
	v_mov_b32_e32 v53, v48
	v_mov_b32_e32 v54, v48
	v_mov_b32_e32 v55, v48
	v_mov_b32_e32 v56, v48
	v_mov_b32_e32 v57, v48
	v_mov_b32_e32 v58, v48
	v_mov_b32_e32 v59, v48
	v_mov_b32_e32 v60, v48
	v_mov_b32_e32 v61, v48
	v_mov_b32_e32 v62, v48
	s_waitcnt vmcnt(7)
	v_cvt_pk_bf16_f32 v20, v20, v21
	v_cvt_pk_bf16_f32 v21, v22, v23
	s_waitcnt vmcnt(6)
	v_cvt_pk_bf16_f32 v22, v24, v25
	v_cvt_pk_bf16_f32 v23, v26, v27
	ds_write_b128 v150, v[20:23]
	s_waitcnt vmcnt(5)
	v_cvt_pk_bf16_f32 v20, v28, v29
	v_cvt_pk_bf16_f32 v21, v30, v31
	s_waitcnt vmcnt(4)
	v_cvt_pk_bf16_f32 v22, v32, v33
	v_cvt_pk_bf16_f32 v23, v34, v35
	global_load_dwordx4 v[108:111], v[42:43], off offset:16 nt
	global_load_dwordx4 v[112:115], v[42:43], off nt
	ds_write_b128 v151, v[20:23] offset:32768
	global_load_dwordx4 v[124:127], v[38:39], off offset:16 nt
	global_load_dwordx4 v[128:131], v[38:39], off nt
	v_and_b32_e32 v25, 24, v19
	v_lshlrev_b32_e32 v19, 4, v18
	v_lshlrev_b32_e32 v21, 4, v14
	v_lshlrev_b32_e32 v14, 1, v18
	v_and_b32_e32 v19, 0xc0, v19
	v_lshlrev_b32_e32 v20, 7, v145
	v_and_b32_e32 v14, 32, v14
	v_lshl_or_b32 v19, v1, 8, v19
	v_xor_b32_e32 v22, 32, v21
	v_xor_b32_e32 v23, 64, v21
	v_xor_b32_e32 v24, 0x60, v21
	v_or3_b32 v26, v19, v14, v25
	v_add_u32_e32 v14, 0, v20
	v_add_u32_e32 v156, v21, v14
	v_add_u32_e32 v155, v22, v14
	v_add_u32_e32 v154, v23, v14
	v_add_u32_e32 v153, v24, v14
	v_add_u32_e32 v14, s17, v152
	v_sub_u32_e32 v157, v14, v149
	v_add_u32_e32 v14, s93, v144
	v_lshrrev_b32_e32 v19, 1, v14
	v_xor_b32_e32 v27, v19, v18
	v_min_i32_e32 v18, 15, v14
	v_ashrrev_i32_e32 v19, 31, v18
	v_lshl_add_u64 v[18:19], s[2:3], 0, v[18:19]
	v_lshlrev_b64 v[18:19], 10, v[18:19]
	v_lshlrev_b32_e32 v14, 4, v27
	v_lshl_add_u64 v[18:19], s[10:11], 0, v[18:19]
	v_and_b32_e32 v14, 0x70, v14
	v_readlane_b32 s10, v250, 31
	v_lshl_add_u64 v[132:133], v[18:19], 0, v[14:15]
	s_add_i32 s17, 0, 0x10400
	v_add_u32_e32 v14, s10, v44
	v_min_i32_e32 v18, 15, v14
	v_ashrrev_i32_e32 v19, 31, v18
	v_lshl_add_u64 v[18:19], s[2:3], 0, v[18:19]
	v_lshlrev_b64 v[18:19], 10, v[18:19]
	v_readlane_b32 s10, v250, 33
	v_lshl_add_u64 v[18:19], s[20:21], 0, v[18:19]
	s_lshl_b32 s18, s10, 1
	v_lshl_add_u64 v[18:19], v[18:19], 0, s[18:19]
	v_lshlrev_b32_e32 v14, 1, v25
	s_add_i32 s10, 0, 0x2000
	v_lshl_add_u64 v[134:135], v[18:19], 0, v[14:15]
	v_add_u32_e32 v14, s10, v20
	v_readlane_b32 s10, v250, 37
	v_add_u32_e32 v158, v21, v14
	v_add_u32_e32 v159, v22, v14
	v_add_u32_e32 v160, v23, v14
	v_add_u32_e32 v161, v24, v14
	v_add_u32_e32 v14, s10, v152
	v_sub_u32_e32 v162, v14, v149
	v_and_b32_e32 v14, 7, v45
	v_lshlrev_b32_e32 v14, 5, v14
	v_lshl_add_u32 v146, v145, 2, s17
	s_add_i32 s17, 0, 0x8000
	s_add_i32 s10, 0, 0xa000
	v_or3_b32 v16, v16, s13, v14
	v_mov_b32_e32 v28, v15
	v_mov_b32_e32 v29, v15
	s_waitcnt lgkmcnt(0)
	v_add_u32_e32 v147, s17, v26
	v_add_u32_e32 v163, s10, v26
	v_lshl_add_u64 v[136:137], s[88:89], 0, v[16:17]
	v_lshl_add_u64 v[138:139], s[90:91], 0, v[16:17]
	v_mov_b32_e32 v14, v15
	v_mov_b32_e32 v16, v15
	v_mov_b32_e32 v17, v15
	v_mov_b32_e32 v18, v15
	v_mov_b32_e32 v19, v15
	v_mov_b32_e32 v20, v15
	v_mov_b32_e32 v21, v15
	v_mov_b32_e32 v22, v15
	v_mov_b32_e32 v23, v15
	v_mov_b32_e32 v24, v15
	v_mov_b32_e32 v25, v15
	v_mov_b32_e32 v26, v15
	v_mov_b32_e32 v27, v15
	v_mov_b64_e32 v[46:47], v[28:29]
	v_mov_b64_e32 v[44:45], v[26:27]
	v_mov_b64_e32 v[42:43], v[24:25]
	v_mov_b64_e32 v[40:41], v[22:23]
	v_mov_b64_e32 v[38:39], v[20:21]
	v_mov_b64_e32 v[36:37], v[18:19]
	v_mov_b64_e32 v[34:35], v[16:17]
	v_mov_b64_e32 v[32:33], v[14:15]
	v_mov_b64_e32 v[30:31], v[28:29]
	v_mov_b32_e32 v63, v48
	s_mov_b32 s13, 0
	v_mov_b32_e32 v148, 0
	s_mov_b64 s[8:9], 0
	v_mov_b64_e32 v[28:29], v[26:27]
	v_mov_b64_e32 v[26:27], v[24:25]
	v_mov_b64_e32 v[24:25], v[22:23]
	v_mov_b64_e32 v[22:23], v[20:21]
	v_mov_b64_e32 v[20:21], v[18:19]
	v_mov_b64_e32 v[18:19], v[16:17]
	v_mov_b64_e32 v[16:17], v[14:15]
	s_waitcnt lgkmcnt(0)
	s_barrier
	s_branch .LBB0_1110
